# pool-fold weight jobs: 8 operand loads per job issued together (on top of the pipelined transpose/convert loop)
# speedup vs baseline: 1.0093x; 1.0093x over previous
.LBB0_63:
	s_andn2_b64 vcc, exec, s[26:27]
	s_cbranch_vccnz .LBB0_45
	v_mov_b32_e32 v1, v226
	s_nop 0
	v_cmp_gt_i32_e32 vcc, s43, v1
	s_and_saveexec_b64 s[26:27], vcc
	s_cbranch_execz .LBB0_69
	s_and_b32 s28, s24, 0x180
	s_lshl_b32 s29, s28, 2
	s_add_u32 s30, s4, s29
	s_addc_u32 s31, s5, 0
	v_lshrrev_b32_e32 v4, 5, v1
	v_and_b32_e32 v5, 31, v1
	v_lshlrev_b32_e32 v5, 4, v5
	v_add_u32_e32 v6, s47, v4
	s_mov_b32 s29, 0x8200
	v_mad_u32_u24 v6, v6, s29, v5
	global_load_dwordx4 v[8:11], v6, s[30:31]
	v_add_u32_e32 v7, 0x82000, v6
	global_load_dwordx4 v[12:15], v7, s[30:31]
	v_add_u32_e32 v7, 0x104000, v6
	global_load_dwordx4 v[16:19], v7, s[30:31]
	v_add_u32_e32 v7, 0x186000, v6
	global_load_dwordx4 v[20:23], v7, s[30:31]
	s_and_b32 s29, s24, 64
	s_lshl_b32 s29, s29, 2
	s_add_u32 s34, s6, s29
	s_addc_u32 s35, s7, 0
	v_lshrrev_b32_e32 v40, 4, v1
	v_and_b32_e32 v41, 15, v1
	v_lshlrev_b32_e32 v41, 4, v41
	v_add_u32_e32 v42, s28, v40
	v_lshl_add_u32 v42, v42, 9, v41
	global_load_dwordx4 v[24:27], v42, s[34:35]
	v_add_u32_e32 v43, 0x4000, v42
	global_load_dwordx4 v[28:31], v43, s[34:35]
	v_add_u32_e32 v43, 0x8000, v42
	global_load_dwordx4 v[32:35], v43, s[34:35]
	v_add_u32_e32 v43, 0xc000, v42
	global_load_dwordx4 v[36:39], v43, s[34:35]
	s_movk_i32 s29, 0x204
	v_mad_u32_u24 v7, v4, s29, v5
	s_waitcnt vmcnt(7)
	ds_write2_b32 v7, v8, v9 offset1:1
	ds_write2_b32 v7, v10, v11 offset0:2 offset1:3
	v_add_u32_e32 v7, 0x2040, v7
	s_waitcnt vmcnt(6)
	ds_write2_b32 v7, v12, v13 offset1:1
	ds_write2_b32 v7, v14, v15 offset0:2 offset1:3
	v_add_u32_e32 v7, 0x2040, v7
	s_waitcnt vmcnt(5)
	ds_write2_b32 v7, v16, v17 offset1:1
	ds_write2_b32 v7, v18, v19 offset0:2 offset1:3
	v_add_u32_e32 v7, 0x2040, v7
	s_waitcnt vmcnt(4)
	ds_write2_b32 v7, v20, v21 offset1:1
	ds_write2_b32 v7, v22, v23 offset0:2 offset1:3
	s_movk_i32 s29, 0x104
	v_mad_u32_u24 v43, v40, s29, v41
	v_add_u32_e32 v43, 0x8100, v43
	s_waitcnt vmcnt(3)
	ds_write2_b32 v43, v24, v25 offset1:1
	ds_write2_b32 v43, v26, v27 offset0:2 offset1:3
	v_add_u32_e32 v43, 0x2080, v43
	s_waitcnt vmcnt(2)
	ds_write2_b32 v43, v28, v29 offset1:1
	ds_write2_b32 v43, v30, v31 offset0:2 offset1:3
	v_add_u32_e32 v43, 0x2080, v43
	s_waitcnt vmcnt(1)
	ds_write2_b32 v43, v32, v33 offset1:1
	ds_write2_b32 v43, v34, v35 offset0:2 offset1:3
	v_add_u32_e32 v43, 0x2080, v43
	s_waitcnt vmcnt(0)
	ds_write2_b32 v43, v36, v37 offset1:1
	ds_write2_b32 v43, v38, v39 offset0:2 offset1:3

.LBB0_213:
	s_andn2_b64 vcc, exec, s[22:23]
	s_cbranch_vccnz .LBB0_195
	v_mov_b32_e32 v0, v226
	s_movk_i32 s0, 0x800
	s_nop 0
	v_cmp_gt_i32_e32 vcc, s0, v0
	s_and_saveexec_b64 s[22:23], vcc
	s_cbranch_execz .LBB0_219
	s_and_b32 s33, s80, 0x180
	s_lshl_b32 s0, s33, 2
	s_add_u32 s24, s8, s0
	s_addc_u32 s25, s9, 0
	v_lshrrev_b32_e32 v4, 5, v0
	v_and_b32_e32 v5, 31, v0
	v_lshlrev_b32_e32 v5, 4, v5
	v_add_u32_e32 v6, s1, v4
	s_mov_b32 s0, 0x8200
	v_mad_u32_u24 v6, v6, s0, v5
	global_load_dwordx4 v[8:11], v6, s[24:25]
	v_add_u32_e32 v7, 0x82000, v6
	global_load_dwordx4 v[12:15], v7, s[24:25]
	v_add_u32_e32 v7, 0x104000, v6
	global_load_dwordx4 v[16:19], v7, s[24:25]
	v_add_u32_e32 v7, 0x186000, v6
	global_load_dwordx4 v[20:23], v7, s[24:25]
	s_and_b32 s0, s80, 64
	s_lshl_b32 s0, s0, 2
	s_add_u32 s26, s30, s0
	s_addc_u32 s27, s31, 0
	v_lshrrev_b32_e32 v40, 4, v0
	v_and_b32_e32 v41, 15, v0
	v_lshlrev_b32_e32 v41, 4, v41
	v_add_u32_e32 v42, s33, v40
	v_lshl_add_u32 v42, v42, 9, v41
	global_load_dwordx4 v[24:27], v42, s[26:27]
	v_add_u32_e32 v43, 0x4000, v42
	global_load_dwordx4 v[28:31], v43, s[26:27]
	v_add_u32_e32 v43, 0x8000, v42
	global_load_dwordx4 v[32:35], v43, s[26:27]
	v_add_u32_e32 v43, 0xc000, v42
	global_load_dwordx4 v[36:39], v43, s[26:27]
	s_movk_i32 s0, 0x204
	v_mad_u32_u24 v7, v4, s0, v5
	s_waitcnt vmcnt(7)
	ds_write2_b32 v7, v8, v9 offset1:1
	ds_write2_b32 v7, v10, v11 offset0:2 offset1:3
	v_add_u32_e32 v7, 0x2040, v7
	s_waitcnt vmcnt(6)
	ds_write2_b32 v7, v12, v13 offset1:1
	ds_write2_b32 v7, v14, v15 offset0:2 offset1:3
	v_add_u32_e32 v7, 0x2040, v7
	s_waitcnt vmcnt(5)
	ds_write2_b32 v7, v16, v17 offset1:1
	ds_write2_b32 v7, v18, v19 offset0:2 offset1:3
	v_add_u32_e32 v7, 0x2040, v7
	s_waitcnt vmcnt(4)
	ds_write2_b32 v7, v20, v21 offset1:1
	ds_write2_b32 v7, v22, v23 offset0:2 offset1:3
	s_movk_i32 s0, 0x104
	v_mad_u32_u24 v43, v40, s0, v41
	v_add_u32_e32 v43, 0x8100, v43
	s_waitcnt vmcnt(3)
	ds_write2_b32 v43, v24, v25 offset1:1
	ds_write2_b32 v43, v26, v27 offset0:2 offset1:3
	v_add_u32_e32 v43, 0x2080, v43
	s_waitcnt vmcnt(2)
	ds_write2_b32 v43, v28, v29 offset1:1
	ds_write2_b32 v43, v30, v31 offset0:2 offset1:3
	v_add_u32_e32 v43, 0x2080, v43
	s_waitcnt vmcnt(1)
	ds_write2_b32 v43, v32, v33 offset1:1
	ds_write2_b32 v43, v34, v35 offset0:2 offset1:3
	v_add_u32_e32 v43, 0x2080, v43
	s_waitcnt vmcnt(0)
	ds_write2_b32 v43, v36, v37 offset1:1
	ds_write2_b32 v43, v38, v39 offset0:2 offset1:3
